# v29
# baseline (speedup 1.0000x reference)
.LBB0_277:
	s_cmp_eq_u32 s52, 0
	s_cbranch_scc1 .Lrnn_conv_c0
	v_lshlrev_b32_e32 v94, 16, v52
	v_and_b32_e32 v95, 0xffff0000, v52
	v_lshlrev_b32_e32 v96, 16, v53
	v_and_b32_e32 v97, 0xffff0000, v53
	v_lshlrev_b32_e32 v98, 16, v54
	v_and_b32_e32 v99, 0xffff0000, v54
	v_lshlrev_b32_e32 v100, 16, v55
	v_and_b32_e32 v101, 0xffff0000, v55
	v_lshlrev_b32_e32 v92, 16, v56
	v_and_b32_e32 v93, 0xffff0000, v56
	v_lshlrev_b32_e32 v102, 16, v57
	v_and_b32_e32 v103, 0xffff0000, v57
	v_lshlrev_b32_e32 v104, 16, v58
	v_and_b32_e32 v105, 0xffff0000, v58
	v_lshlrev_b32_e32 v106, 16, v59
	v_and_b32_e32 v107, 0xffff0000, v59
	v_lshlrev_b32_e32 v110, 16, v60
	v_and_b32_e32 v111, 0xffff0000, v60
	v_lshlrev_b32_e32 v112, 16, v61
	v_and_b32_e32 v113, 0xffff0000, v61
	v_lshlrev_b32_e32 v114, 16, v62
	v_and_b32_e32 v115, 0xffff0000, v62
	v_lshlrev_b32_e32 v116, 16, v63
	v_and_b32_e32 v117, 0xffff0000, v63
	v_lshlrev_b32_e32 v108, 16, v64
	v_and_b32_e32 v109, 0xffff0000, v64
	v_lshlrev_b32_e32 v122, 16, v65
	v_and_b32_e32 v123, 0xffff0000, v65
	v_lshlrev_b32_e32 v120, 16, v66
	v_and_b32_e32 v121, 0xffff0000, v66
	v_lshlrev_b32_e32 v118, 16, v67
	v_and_b32_e32 v119, 0xffff0000, v67
	s_branch .LBB0_285
